# attention QK: 12 K-fragment LDS reads prefetched into the (dead) K/V staging registers, counted lgkmcnt waits, both local-mode copies
# baseline (speedup 1.0000x reference)
; #define LAS __attribute__((address_space(3)))
; __device__ __forceinline__ void store_kv(LAS unsigned char* lds, const u32x4 (&val)[14], int tid) {
; #pragma unroll
;     for (int i = 0; i < 14; ++i) {
;         const int piece = tid + 512 * i, slot = piece >> 4, sub = piece & 15;
;         const int off = (sub < 8) ? (L_K + sub * KCS + slot * 16) : (L_V + ((sub - 8) >> 2) * VDS + slot * 64 + ((sub - 8) & 3) * 16);
;         *(LAS u32x4*)(lds + off) = val[i];
;     }
; }
; __device__ __forceinline__ void load_q(bf16x8 (&qr)[4], const UD& x, const unsigned char* ws, int wid, int r32, int hi) {
;     int d, L, cls, t0, sbase; wave_geo(x, wid, d, L, cls, t0, sbase);
;     const bf16_t* Qb = (const bf16_t*)(ws + off_q(x.b));
;     const size_t qtok = (size_t)x.b * SEQ + (size_t)(t0 + r32) * d + cls;
; #pragma unroll
;     for (int d0 = 0; d0 < 4; ++d0) qr[d0] = *(const bf16x8*)(Qb + qtok * AW + x.h * HD + d0 * 16 + hi * 8);
; }
; __device__ __forceinline__ void compute_a(LAS unsigned char* lds, const UD& x, const bf16x8 (&qr)[4], int wid, int lane, u32x4 (&pw)[10], float& mx_o, float& l_o) {
;     const int r32 = lane & 31, hi = lane >> 5;
;     int d, L, cls, t0, sbase; wave_geo(x, wid, d, L, cls, t0, sbase);
;     f32x16 s[5];
; #pragma unroll
;     for (int ht = 0; ht < 5; ++ht) {
;         const LAS unsigned char* kb = lds + L_K + hi * KCS + (sbase + 32 * ht + r32) * 16;
;         f32x16 a = {};
; #pragma unroll
;         for (int d0 = 0; d0 < 4; ++d0) { const bf16x8 kf = *(const LAS bf16x8*)(kb + d0 * 2 * KCS); a = __builtin_amdgcn_mfma_f32_32x32x16_bf16(kf, qr[d0], a, 0, 0, 0); }
;         s[ht] = a;
;     }
;     {
;         const int dq = r32 - 4 * hi;
; #pragma unroll
;         for (int r = 0; r < 16; ++r) { const int cr = (r & 3) + 8 * (r >> 2); s[0][r] = (cr >= dq) ? s[0][r] : -INFINITY; s[4][r] = (cr <= dq) ? s[4][r] : -INFINITY; }
;         if (t0 < 64) {
; #pragma unroll
;             for (int r = 0; r < 16; ++r) s[0][r] = -INFINITY;
;             if (t0 < 32) {
; #pragma unroll
;                 for (int r = 0; r < 16; ++r) s[1][r] = -INFINITY;
;             }
.LBB0_634:
	s_ashr_i32 s1, s18, 4
	s_mul_hi_i32 s0, s1, 0x2aaaaaab
	s_lshr_b32 s4, s0, 31
	s_ashr_i32 s0, s0, 1
	s_add_i32 s0, s0, s4
	s_mul_i32 s4, s0, 12
	s_bfe_u32 s13, s18, 0x10003
	s_sub_i32 s20, s1, s4
	s_cmp_eq_u32 s13, 0
	s_cselect_b64 s[22:23], -1, 0
	s_and_b64 s[16:17], s[22:23], exec
	s_cselect_b32 s11, 2, 4
	s_cselect_b32 s21, s45, s9
	s_cselect_b32 s12, s10, s8
	s_ashr_i32 s1, s0, 31
	s_lshl_b64 s[16:17], s[0:1], 23
	v_readlane_b32 s4, v252, 1
	v_cndmask_b32_e64 v0, v214, v194, s[22:23]
	v_readlane_b32 s5, v252, 2
	s_add_u32 s16, s4, s16
	v_or_b32_e32 v2, s12, v160
	s_addc_u32 s17, s5, s17
	s_lshl_b64 s[46:47], s[0:1], 11
	v_ashrrev_i32_e32 v3, 31, v2
	v_ashrrev_i32_e32 v1, 31, v0
	v_lshlrev_b64 v[2:3], s11, v[2:3]
	v_lshl_add_u64 v[150:151], s[46:47], 0, v[0:1]
	v_lshl_add_u64 v[152:153], v[150:151], 0, v[2:3]
	v_mov_b64_e32 v[0:1], s[16:17]
	v_mad_u64_u32 v[0:1], s[16:17], v152, s40, v[0:1]
	s_lshl_b32 s16, s20, 6
	v_mad_i32_i24 v1, v153, s40, v1
	s_ashr_i32 s17, s16, 31
	v_lshl_add_u64 v[0:1], s[16:17], 1, v[0:1]
	v_mov_b32_e32 v147, v81
	v_lshl_add_u64 v[0:1], v[0:1], 0, v[146:147]
	s_mov_b64 s[4:5], 0xc000000
	s_brev_b32 s1, 48
	v_lshl_add_u64 v[2:3], v[0:1], 0, s[4:5]
	v_add_co_u32_e32 v0, vcc, s1, v0
	s_cmp_gt_i32 s12, 63
	s_nop 0
	v_addc_co_u32_e32 v1, vcc, 0, v1, vcc
	global_load_dwordx4 v[48:51], v[0:1], off
	global_load_dwordx4 v[234:237], v[2:3], off offset:32
	global_load_dwordx4 v[242:245], v[2:3], off offset:64
	global_load_dwordx4 v[132:135], v[2:3], off offset:96
	v_or_b32_e32 v0, s21, v160
	v_lshl_add_u32 v80, v0, 4, v161
	s_waitcnt vmcnt(12)
	ds_write_b128 v215, v[84:87]
	ds_write_b128 v216, v[88:91]
	ds_write_b128 v217, v[92:95]
	ds_write_b128 v218, v[96:99]
	ds_write_b128 v219, v[100:103]
	ds_write_b128 v220, v[104:107]
	ds_write_b128 v221, v[108:111]
	ds_write_b128 v222, v[112:115]
	s_waitcnt vmcnt(11)
	ds_write_b128 v223, v[116:119]
	s_waitcnt vmcnt(10)
	ds_write_b128 v224, v[120:123]
	s_waitcnt vmcnt(5)
	ds_write_b128 v225, v[124:127]
	s_waitcnt vmcnt(4)
	ds_write_b128 v226, v[128:131]
	ds_write_b128 v227, v[238:241]
	ds_write_b128 v228, v[238:241]
	s_waitcnt lgkmcnt(0)
	s_barrier
	ds_read_b128 v[84:87], v80
	ds_read_b128 v[88:91], v80 offset:14368
	ds_read_b128 v[92:95], v80 offset:28736
	ds_read_b128 v[96:99], v80 offset:43104
	ds_read_b128 v[100:103], v80 offset:512
	ds_read_b128 v[104:107], v80 offset:14880
	ds_read_b128 v[108:111], v80 offset:29248
	ds_read_b128 v[112:115], v80 offset:43616
	ds_read_b128 v[116:119], v80 offset:1024
	ds_read_b128 v[120:123], v80 offset:15392
	ds_read_b128 v[124:127], v80 offset:29760
	ds_read_b128 v[128:131], v80 offset:44128
	s_waitcnt vmcnt(3) lgkmcnt(11)
	v_mfma_f32_32x32x16_bf16 v[64:79], v[84:87], v[48:51], 0
	ds_read_b128 v[84:87], v80 offset:1536
	s_waitcnt vmcnt(2) lgkmcnt(11)
	v_mfma_f32_32x32x16_bf16 v[64:79], v[88:91], v[234:237], v[64:79]
	ds_read_b128 v[88:91], v80 offset:15904
	s_waitcnt vmcnt(1) lgkmcnt(11)
	v_mfma_f32_32x32x16_bf16 v[64:79], v[92:95], v[242:245], v[64:79]
	ds_read_b128 v[92:95], v80 offset:30272
	s_waitcnt vmcnt(0) lgkmcnt(11)
	v_mfma_f32_32x32x16_bf16 v[64:79], v[96:99], v[132:135], v[64:79]
	ds_read_b128 v[96:99], v80 offset:44640
	s_waitcnt lgkmcnt(11)
	v_mfma_f32_32x32x16_bf16 v[32:47], v[100:103], v[48:51], 0
	ds_read_b128 v[100:103], v80 offset:2048
	s_waitcnt lgkmcnt(11)
	v_mfma_f32_32x32x16_bf16 v[32:47], v[104:107], v[234:237], v[32:47]
	ds_read_b128 v[104:107], v80 offset:16416
	s_waitcnt lgkmcnt(11)
	v_mfma_f32_32x32x16_bf16 v[32:47], v[108:111], v[242:245], v[32:47]
	ds_read_b128 v[108:111], v80 offset:30784
	s_waitcnt lgkmcnt(11)
	v_mfma_f32_32x32x16_bf16 v[32:47], v[112:115], v[132:135], v[32:47]
	ds_read_b128 v[112:115], v80 offset:45152
	s_waitcnt lgkmcnt(11)
	v_mfma_f32_32x32x16_bf16 v[16:31], v[116:119], v[48:51], 0
	s_waitcnt lgkmcnt(10)
	v_mfma_f32_32x32x16_bf16 v[16:31], v[120:123], v[234:237], v[16:31]
	s_waitcnt lgkmcnt(9)
	v_mfma_f32_32x32x16_bf16 v[16:31], v[124:127], v[242:245], v[16:31]
	s_waitcnt lgkmcnt(8)
	v_mfma_f32_32x32x16_bf16 v[16:31], v[128:131], v[132:135], v[16:31]
	s_waitcnt lgkmcnt(7)
	v_mfma_f32_32x32x16_bf16 v[0:15], v[84:87], v[48:51], 0
	s_waitcnt lgkmcnt(6)
	v_mfma_f32_32x32x16_bf16 v[0:15], v[88:91], v[234:237], v[0:15]
	s_waitcnt lgkmcnt(5)
	v_mfma_f32_32x32x16_bf16 v[0:15], v[92:95], v[242:245], v[0:15]
	s_waitcnt lgkmcnt(4)
	v_mfma_f32_32x32x16_bf16 v[0:15], v[96:99], v[132:135], v[0:15]
	s_waitcnt lgkmcnt(3)
	v_mfma_f32_32x32x16_bf16 v[48:63], v[100:103], v[48:51], 0
	s_waitcnt lgkmcnt(2)
	v_mfma_f32_32x32x16_bf16 v[48:63], v[104:107], v[234:237], v[48:63]
	s_waitcnt lgkmcnt(1)
	v_mfma_f32_32x32x16_bf16 v[48:63], v[108:111], v[242:245], v[48:63]
	s_waitcnt lgkmcnt(0)
	v_mfma_f32_32x32x16_bf16 v[48:63], v[112:115], v[132:135], v[48:63]
	s_cbranch_scc1 .LBB0_638
	s_cmp_gt_i32 s12, 31
	s_cbranch_scc1 .LBB0_637
	v_mov_b32_e32 v47, 0xff800000
	v_mov_b32_e32 v46, v47
	v_mov_b32_e32 v45, v47
	v_mov_b32_e32 v44, v47
	v_mov_b32_e32 v43, v47
	v_mov_b32_e32 v42, v47
	v_mov_b32_e32 v41, v47
	v_mov_b32_e32 v40, v47
	v_mov_b32_e32 v39, v47
	v_mov_b32_e32 v38, v47
	v_mov_b32_e32 v37, v47
	v_mov_b32_e32 v36, v47
	v_mov_b32_e32 v35, v47
	v_mov_b32_e32 v34, v47
	v_mov_b32_e32 v33, v47
	v_mov_b32_e32 v32, v47

; #define LAS __attribute__((address_space(3)))
; __device__ __forceinline__ void store_kv(LAS unsigned char* lds, const u32x4 (&val)[14], int tid) {
; #pragma unroll
;     for (int i = 0; i < 14; ++i) {
;         const int piece = tid + 512 * i, slot = piece >> 4, sub = piece & 15;
;         const int off = (sub < 8) ? (L_K + sub * KCS + slot * 16) : (L_V + ((sub - 8) >> 2) * VDS + slot * 64 + ((sub - 8) & 3) * 16);
;         *(LAS u32x4*)(lds + off) = val[i];
;     }
; }
; __device__ __forceinline__ void load_q(bf16x8 (&qr)[4], const UD& x, const unsigned char* ws, int wid, int r32, int hi) {
;     int d, L, cls, t0, sbase; wave_geo(x, wid, d, L, cls, t0, sbase);
;     const bf16_t* Qb = (const bf16_t*)(ws + off_q(x.b));
;     const size_t qtok = (size_t)x.b * SEQ + (size_t)(t0 + r32) * d + cls;
; #pragma unroll
;     for (int d0 = 0; d0 < 4; ++d0) qr[d0] = *(const bf16x8*)(Qb + qtok * AW + x.h * HD + d0 * 16 + hi * 8);
; }
; __device__ __forceinline__ void compute_a(LAS unsigned char* lds, const UD& x, const bf16x8 (&qr)[4], int wid, int lane, u32x4 (&pw)[10], float& mx_o, float& l_o) {
;     const int r32 = lane & 31, hi = lane >> 5;
;     int d, L, cls, t0, sbase; wave_geo(x, wid, d, L, cls, t0, sbase);
;     f32x16 s[5];
; #pragma unroll
;     for (int ht = 0; ht < 5; ++ht) {
;         const LAS unsigned char* kb = lds + L_K + hi * KCS + (sbase + 32 * ht + r32) * 16;
;         f32x16 a = {};
; #pragma unroll
;         for (int d0 = 0; d0 < 4; ++d0) { const bf16x8 kf = *(const LAS bf16x8*)(kb + d0 * 2 * KCS); a = __builtin_amdgcn_mfma_f32_32x32x16_bf16(kf, qr[d0], a, 0, 0, 0); }
;         s[ht] = a;
;     }
;     {
;         const int dq = r32 - 4 * hi;
; #pragma unroll
;         for (int r = 0; r < 16; ++r) { const int cr = (r & 3) + 8 * (r >> 2); s[0][r] = (cr >= dq) ? s[0][r] : -INFINITY; s[4][r] = (cr <= dq) ? s[4][r] : -INFINITY; }
;         if (t0 < 64) {
; #pragma unroll
;             for (int r = 0; r < 16; ++r) s[0][r] = -INFINITY;
;             if (t0 < 32) {
; #pragma unroll
;                 for (int r = 0; r < 16; ++r) s[1][r] = -INFINITY;
;             }
.LBB0_903:
	s_ashr_i32 s1, s18, 3
	s_mul_hi_i32 s0, s1, 0x2aaaaaab
	s_lshr_b32 s14, s0, 31
	s_ashr_i32 s0, s0, 1
	s_add_i32 s0, s0, s14
	s_mul_i32 s14, s0, 12
	s_sub_i32 s22, s1, s14
	s_lshl_b32 s1, s18, 8
	s_and_b32 s21, s1, 0x700
	s_ashr_i32 s1, s0, 31
	s_lshl_b64 s[14:15], s[0:1], 23
	v_readlane_b32 s16, v252, 1
	v_readlane_b32 s17, v252, 2
	s_add_u32 s16, s16, s14
	v_add_u32_e32 v0, s21, v150
	s_addc_u32 s17, s17, s15
	s_lshl_b64 s[14:15], s[0:1], 11
	v_ashrrev_i32_e32 v1, 31, v0
	v_lshl_add_u64 v[0:1], s[14:15], 0, v[0:1]
	v_mov_b64_e32 v[2:3], s[16:17]
	v_mad_u64_u32 v[2:3], s[16:17], v0, s40, v[2:3]
	s_lshl_b32 s16, s22, 6
	v_mad_i32_i24 v3, v1, s40, v3
	s_ashr_i32 s17, s16, 31
	v_lshl_add_u64 v[0:1], s[16:17], 1, v[2:3]
	v_mov_b32_e32 v143, v81
	v_lshl_add_u64 v[0:1], v[0:1], 0, v[142:143]
	s_mov_b64 s[24:25], 0xc000000
	s_brev_b32 s19, 48
	v_lshl_add_u64 v[2:3], v[0:1], 0, s[24:25]
	v_add_co_u32_e32 v0, vcc, s19, v0
	s_add_i32 s20, s21, s80
	s_nop 0
	v_addc_co_u32_e32 v1, vcc, 0, v1, vcc
	global_load_dwordx4 v[48:51], v[0:1], off
	global_load_dwordx4 v[232:235], v[2:3], off offset:32
	global_load_dwordx4 v[242:245], v[2:3], off offset:64
	global_load_dwordx4 v[246:249], v[2:3], off offset:96
	s_waitcnt vmcnt(4)
	ds_write_b128 v214, v[84:87]
	ds_write_b128 v215, v[88:91]
	ds_write_b128 v216, v[92:95]
	ds_write_b128 v217, v[96:99]
	ds_write_b128 v218, v[100:103]
	ds_write_b128 v219, v[104:107]
	ds_write_b128 v220, v[108:111]
	ds_write_b128 v221, v[112:115]
	ds_write_b128 v222, v[116:119]
	ds_write_b128 v223, v[120:123]
	ds_write_b128 v224, v[124:127]
	ds_write_b128 v225, v[128:131]
	ds_write_b128 v226, v[238:241]
	ds_write_b128 v227, v[238:241]
	s_waitcnt lgkmcnt(0)
	s_barrier
	ds_read_b128 v[84:87], v228
	ds_read_b128 v[88:91], v228 offset:14368
	ds_read_b128 v[92:95], v228 offset:28736
	ds_read_b128 v[96:99], v228 offset:43104
	ds_read_b128 v[100:103], v228 offset:512
	ds_read_b128 v[104:107], v228 offset:14880
	ds_read_b128 v[108:111], v228 offset:29248
	ds_read_b128 v[112:115], v228 offset:43616
	ds_read_b128 v[116:119], v228 offset:1024
	ds_read_b128 v[120:123], v228 offset:15392
	ds_read_b128 v[124:127], v228 offset:29760
	ds_read_b128 v[128:131], v228 offset:44128
	s_cmp_gt_i32 s20, 63
	s_waitcnt vmcnt(3) lgkmcnt(11)
	v_mfma_f32_32x32x16_bf16 v[64:79], v[84:87], v[48:51], 0
	ds_read_b128 v[84:87], v228 offset:1536
	s_waitcnt vmcnt(2) lgkmcnt(11)
	v_mfma_f32_32x32x16_bf16 v[64:79], v[88:91], v[232:235], v[64:79]
	ds_read_b128 v[88:91], v228 offset:15904
	s_waitcnt vmcnt(1) lgkmcnt(11)
	v_mfma_f32_32x32x16_bf16 v[64:79], v[92:95], v[242:245], v[64:79]
	ds_read_b128 v[92:95], v228 offset:30272
	s_waitcnt vmcnt(0) lgkmcnt(11)
	v_mfma_f32_32x32x16_bf16 v[64:79], v[96:99], v[246:249], v[64:79]
	ds_read_b128 v[96:99], v228 offset:44640
	s_waitcnt lgkmcnt(11)
	v_mfma_f32_32x32x16_bf16 v[32:47], v[100:103], v[48:51], 0
	ds_read_b128 v[100:103], v228 offset:2048
	s_waitcnt lgkmcnt(11)
	v_mfma_f32_32x32x16_bf16 v[32:47], v[104:107], v[232:235], v[32:47]
	ds_read_b128 v[104:107], v228 offset:16416
	s_waitcnt lgkmcnt(11)
	v_mfma_f32_32x32x16_bf16 v[32:47], v[108:111], v[242:245], v[32:47]
	ds_read_b128 v[108:111], v228 offset:30784
	s_waitcnt lgkmcnt(11)
	v_mfma_f32_32x32x16_bf16 v[32:47], v[112:115], v[246:249], v[32:47]
	ds_read_b128 v[112:115], v228 offset:45152
	s_waitcnt lgkmcnt(11)
	v_mfma_f32_32x32x16_bf16 v[16:31], v[116:119], v[48:51], 0
	s_waitcnt lgkmcnt(10)
	v_mfma_f32_32x32x16_bf16 v[16:31], v[120:123], v[232:235], v[16:31]
	s_waitcnt lgkmcnt(9)
	v_mfma_f32_32x32x16_bf16 v[16:31], v[124:127], v[242:245], v[16:31]
	s_waitcnt lgkmcnt(8)
	v_mfma_f32_32x32x16_bf16 v[16:31], v[128:131], v[246:249], v[16:31]
	s_waitcnt lgkmcnt(7)
	v_mfma_f32_32x32x16_bf16 v[0:15], v[84:87], v[48:51], 0
	s_waitcnt lgkmcnt(6)
	v_mfma_f32_32x32x16_bf16 v[0:15], v[88:91], v[232:235], v[0:15]
	s_waitcnt lgkmcnt(5)
	v_mfma_f32_32x32x16_bf16 v[0:15], v[92:95], v[242:245], v[0:15]
	s_waitcnt lgkmcnt(4)
	v_mfma_f32_32x32x16_bf16 v[0:15], v[96:99], v[246:249], v[0:15]
	s_waitcnt lgkmcnt(3)
	v_mfma_f32_32x32x16_bf16 v[48:63], v[100:103], v[48:51], 0
	s_waitcnt lgkmcnt(2)
	v_mfma_f32_32x32x16_bf16 v[48:63], v[104:107], v[232:235], v[48:63]
	s_waitcnt lgkmcnt(1)
	v_mfma_f32_32x32x16_bf16 v[48:63], v[108:111], v[242:245], v[48:63]
	s_waitcnt lgkmcnt(0)
	v_mfma_f32_32x32x16_bf16 v[48:63], v[112:115], v[246:249], v[48:63]
	s_cbranch_scc1 .LBB0_908
	s_cmp_gt_i32 s20, 31
	s_cbranch_scc1 .LBB0_906
	v_mov_b32_e32 v47, 0xff800000
	v_mov_b32_e32 v46, v47
	v_mov_b32_e32 v45, v47
	v_mov_b32_e32 v44, v47
	v_mov_b32_e32 v43, v47
	v_mov_b32_e32 v42, v47
	v_mov_b32_e32 v41, v47
	v_mov_b32_e32 v40, v47
	v_mov_b32_e32 v39, v47
	v_mov_b32_e32 v38, v47
	v_mov_b32_e32 v37, v47
	v_mov_b32_e32 v36, v47
	v_mov_b32_e32 v35, v47
	v_mov_b32_e32 v34, v47
	v_mov_b32_e32 v33, v47
	v_mov_b32_e32 v32, v47
